# final rms-norm loop: gain vector hoisted out of the row loop, all six row loads in flight before the first use
# speedup vs baseline: 1.0973x; 1.0017x over previous
; #define ltid() ltid_(swave)
; DEV void final_norm_phase(CParams& p, int vb, int nb, const int swave) {
;   const int lane = ltid() & 63, w = ltid() >> 6;
;   const float* ssq = (const float*)(p.ws + W_SSQ);
;   const float* g = p.in[29];
;   for (int m = vb * 4 + w; m < MTOK; m += nb * 4) {
;     const float rs = rscale_of(ssq, m);
;     float* row = p.out + (size_t)m * DM;
; #pragma unroll
;     for (int i = 0; i < 4; ++i) {
;       const int c = i * 256 + lane * 4;
;       f32x4 v = *(const f32x4*)(row + c); const f32x4 gv = *(const f32x4*)(g + c);
;       v[0] *= rs * gv[0]; v[1] *= rs * gv[1]; v[2] *= rs * gv[2]; v[3] *= rs * gv[3];
;       *(f32x4*)(row + c) = v;
;     }
;   }
.LBB0_1203:
	v_mov_b32_e32 v0, 0
	v_mov_b32_e32 v2, 0
	v_readlane_b32 s0, v255, 0
	v_mbcnt_lo_u32_b32 v2, -1, v2
	v_mbcnt_hi_u32_b32 v2, -1, v2
	v_or_b32_e32 v2, s0, v2
	v_ashrrev_i32_e32 v2, 6, v2
	v_readlane_b32 s8, v255, 2
	s_mov_b32 s0, 0x8080
	v_mov_b32_e32 v1, 0
	v_add_u32_e32 v6, s8, v2
	v_cmp_gt_i32_e32 vcc, s0, v6
	v_readlane_b32 s9, v255, 3
	s_and_saveexec_b64 s[0:1], vcc
	s_cbranch_execz .LBB0_1206
	s_load_dwordx4 s[4:7], s[64:65], 0xe8
	s_load_dwordx2 s[2:3], s[64:65], 0xf8
	v_mbcnt_lo_u32_b32 v0, -1, v0
	v_ashrrev_i32_e32 v3, 31, v2
	s_ashr_i32 s9, s8, 31
	v_mbcnt_hi_u32_b32 v7, -1, v0
	v_lshl_add_u64 v[4:5], v[2:3], 0, s[8:9]
	s_lshl_b32 s0, s11, 2
	v_lshlrev_b32_e32 v0, 4, v7
	v_lshlrev_b64 v[2:3], 5, v[4:5]
	v_lshlrev_b64 v[4:5], 12, v[4:5]
	v_and_b32_e32 v7, 63, v7
	v_and_b32_e32 v0, 0x3f0, v0
	s_waitcnt lgkmcnt(0)
	v_lshl_add_u64 v[2:3], s[2:3], 0, v[2:3]
	s_mov_b64 s[2:3], 0xa281000
	s_ashr_i32 s1, s0, 31
	v_lshl_or_b32 v4, v7, 4, v4
	v_lshl_add_u64 v[0:1], s[4:5], 0, v[0:1]
	v_lshl_add_u64 v[2:3], v[2:3], 0, s[2:3]
	s_lshl_b64 s[2:3], s[0:1], 5
	v_lshl_add_u64 v[4:5], s[6:7], 0, v[4:5]
	s_lshl_b64 s[4:5], s[0:1], 12
	s_mov_b64 s[6:7], 0
	v_mov_b32_e32 v7, 0x358637bd
	s_mov_b32 s1, 0x800000
	s_mov_b32 s8, 0x807f
	global_load_dwordx4 v[32:35], v[0:1], off
	global_load_dwordx4 v[36:39], v[0:1], off offset:1024
	global_load_dwordx4 v[40:43], v[0:1], off offset:2048
	global_load_dwordx4 v[44:47], v[0:1], off offset:3072
.LBB0_1205:
	global_load_dwordx4 v[8:11], v[2:3], off
	global_load_dwordx4 v[12:15], v[2:3], off offset:16
	global_load_dwordx4 v[48:51], v[4:5], off
	global_load_dwordx4 v[52:55], v[4:5], off offset:1024
	global_load_dwordx4 v[56:59], v[4:5], off offset:2048
	global_load_dwordx4 v[60:63], v[4:5], off offset:3072
	v_add_u32_e32 v6, s0, v6
	v_lshl_add_u64 v[2:3], v[2:3], 0, s[2:3]
	s_waitcnt vmcnt(5)
	v_mov_b32_e32 v28, v9
	v_mov_b32_e32 v29, v10
	v_mov_b32_e32 v9, v11
	s_waitcnt vmcnt(4)
	v_mov_b32_e32 v10, v14
	v_mov_b32_e32 v11, v12
	v_mov_b32_e32 v12, v15
	v_pk_add_f32 v[8:9], v[28:29], v[8:9]
	v_pk_add_f32 v[10:11], v[10:11], v[12:13]
	v_add_f32_e32 v8, v8, v9
	v_add_f32_e32 v8, v8, v11
	v_add_f32_e32 v8, v10, v8
	v_fmamk_f32 v8, v8, 0x3a800000, v7
	v_mul_f32_e32 v9, 0x4b800000, v8
	v_cmp_gt_f32_e32 vcc, s1, v8
	s_nop 1
	v_cndmask_b32_e32 v8, v8, v9, vcc
	v_rsq_f32_e32 v8, v8
	s_nop 0
	v_mul_f32_e32 v9, 0x45800000, v8
	v_cndmask_b32_e32 v28, v8, v9, vcc
	v_cmp_lt_i32_e32 vcc, s8, v6
	s_or_b64 s[6:7], vcc, s[6:7]
	s_waitcnt vmcnt(3)
	v_pk_mul_f32 v[8:9], v[32:33], v[28:29] op_sel_hi:[1,0]
	v_pk_mul_f32 v[10:11], v[34:35], v[28:29] op_sel_hi:[1,0]
	v_pk_mul_f32 v[8:9], v[48:49], v[8:9]
	v_pk_mul_f32 v[10:11], v[50:51], v[10:11]
	global_store_dwordx4 v[4:5], v[8:11], off
	s_waitcnt vmcnt(3)
	v_pk_mul_f32 v[12:13], v[36:37], v[28:29] op_sel_hi:[1,0]
	v_pk_mul_f32 v[14:15], v[38:39], v[28:29] op_sel_hi:[1,0]
	v_pk_mul_f32 v[12:13], v[52:53], v[12:13]
	v_pk_mul_f32 v[14:15], v[54:55], v[14:15]
	global_store_dwordx4 v[4:5], v[12:15], off offset:1024
	s_waitcnt vmcnt(3)
	v_pk_mul_f32 v[16:17], v[40:41], v[28:29] op_sel_hi:[1,0]
	v_pk_mul_f32 v[18:19], v[42:43], v[28:29] op_sel_hi:[1,0]
	v_pk_mul_f32 v[16:17], v[56:57], v[16:17]
	v_pk_mul_f32 v[18:19], v[58:59], v[18:19]
	global_store_dwordx4 v[4:5], v[16:19], off offset:2048
	s_waitcnt vmcnt(3)
	v_pk_mul_f32 v[20:21], v[44:45], v[28:29] op_sel_hi:[1,0]
	v_pk_mul_f32 v[22:23], v[46:47], v[28:29] op_sel_hi:[1,0]
	v_pk_mul_f32 v[20:21], v[60:61], v[20:21]
	v_pk_mul_f32 v[22:23], v[62:63], v[22:23]
	global_store_dwordx4 v[4:5], v[20:23], off offset:3072
	v_lshl_add_u64 v[4:5], v[4:5], 0, s[4:5]
	s_andn2_b64 exec, exec, s[6:7]
	s_cbranch_execnz .LBB0_1205
